# speedup vs baseline: 1.0012x; 1.0012x over previous
; __device__ __forceinline__ void partialSM(f32x16& p0, f32x16& p1, float& m_reg, float& mn, float& alpha) {
;   constexpr float C = SCALE * 1.4426950408889634f;
;   float pmax = p0[0]; for (int r = 1; r < 16; ++r) pmax = fmaxf(pmax, p0[r]); for (int r = 0; r < 16; ++r) pmax = fmaxf(pmax, p1[r]);
;   { auto rr = __builtin_amdgcn_permlane32_swap(__float_as_uint(pmax), __float_as_uint(pmax), false, false);
;     pmax = fmaxf(__uint_as_float(rr[0]), __uint_as_float(rr[1])); }
;   if (__builtin_expect(__all(pmax - m_reg <= THR / SCALE), 1)) { mn = m_reg; alpha = 1.f; }
.Lat_x_top:
	s_add_i32 s8, s13, -2
	s_and_b32 s25, s8, 1
	s_lshl_b32 s24, s25, 14
	s_setprio 1
	s_waitcnt lgkmcnt(5)
	v_mfma_f32_16x16x32_bf16 v[130:133], v[194:197], v[162:165], v[236:239]
	v_mfma_f32_16x16x32_bf16 v[134:137], v[194:197], v[178:181], v[240:243]
	ds_read_b128 v[194:197], v247 offset:8192
	s_waitcnt lgkmcnt(5)
	v_mfma_f32_16x16x32_bf16 v[138:141], v[198:201], v[162:165], v[236:239]
	v_mfma_f32_16x16x32_bf16 v[142:145], v[198:201], v[178:181], v[240:243]
	ds_read_b128 v[198:201], v247 offset:12288
	s_waitcnt lgkmcnt(5)
	v_mfma_f32_16x16x32_bf16 v[146:149], v[202:205], v[162:165], v[236:239]
	v_mfma_f32_16x16x32_bf16 v[150:153], v[202:205], v[178:181], v[240:243]
	ds_read_b128 v[202:205], v228
	s_waitcnt lgkmcnt(5)
	v_mfma_f32_16x16x32_bf16 v[154:157], v[206:209], v[162:165], v[236:239]
	v_mfma_f32_16x16x32_bf16 v[158:161], v[206:209], v[178:181], v[240:243]
	ds_read_b128 v[206:209], v228 offset:4096
	s_waitcnt lgkmcnt(5)
	v_mfma_f32_16x16x32_bf16 v[130:133], v[210:213], v[166:169], v[130:133]
	v_mfma_f32_16x16x32_bf16 v[134:137], v[210:213], v[182:185], v[134:137]
	ds_read_b128 v[210:213], v228 offset:8192
	s_waitcnt lgkmcnt(5)
	v_mfma_f32_16x16x32_bf16 v[138:141], v[214:217], v[166:169], v[138:141]
	v_mfma_f32_16x16x32_bf16 v[142:145], v[214:217], v[182:185], v[142:145]
	ds_read_b128 v[214:217], v228 offset:12288
	s_waitcnt lgkmcnt(5)
	v_mfma_f32_16x16x32_bf16 v[146:149], v[194:197], v[166:169], v[146:149]
	v_mfma_f32_16x16x32_bf16 v[150:153], v[194:197], v[182:185], v[150:153]
	ds_read_b128 v[194:197], v245
	s_waitcnt lgkmcnt(5)
	v_mfma_f32_16x16x32_bf16 v[154:157], v[198:201], v[166:169], v[154:157]
	v_mfma_f32_16x16x32_bf16 v[158:161], v[198:201], v[182:185], v[158:161]
	ds_read_b128 v[198:201], v245 offset:4096
	s_waitcnt lgkmcnt(5)
	v_mfma_f32_16x16x32_bf16 v[130:133], v[202:205], v[170:173], v[130:133]
	v_mfma_f32_16x16x32_bf16 v[134:137], v[202:205], v[186:189], v[134:137]
	ds_read_b128 v[202:205], v245 offset:8192
	s_waitcnt lgkmcnt(5)
	v_mfma_f32_16x16x32_bf16 v[138:141], v[206:209], v[170:173], v[138:141]
	v_mfma_f32_16x16x32_bf16 v[142:145], v[206:209], v[186:189], v[142:145]
	ds_read_b128 v[206:209], v245 offset:12288
	s_waitcnt lgkmcnt(5)
	v_mfma_f32_16x16x32_bf16 v[146:149], v[210:213], v[170:173], v[146:149]
	v_mfma_f32_16x16x32_bf16 v[150:153], v[210:213], v[186:189], v[150:153]
	s_waitcnt lgkmcnt(4)
	v_mfma_f32_16x16x32_bf16 v[154:157], v[214:217], v[170:173], v[154:157]
	v_mfma_f32_16x16x32_bf16 v[158:161], v[214:217], v[186:189], v[158:161]
	s_waitcnt lgkmcnt(3)
	v_mfma_f32_16x16x32_bf16 v[130:133], v[194:197], v[174:177], v[130:133]
	v_mfma_f32_16x16x32_bf16 v[134:137], v[194:197], v[190:193], v[134:137]
	s_waitcnt lgkmcnt(2)
	v_mfma_f32_16x16x32_bf16 v[138:141], v[198:201], v[174:177], v[138:141]
	v_mfma_f32_16x16x32_bf16 v[142:145], v[198:201], v[190:193], v[142:145]
	s_waitcnt lgkmcnt(1)
	v_mfma_f32_16x16x32_bf16 v[146:149], v[202:205], v[174:177], v[146:149]
	v_mfma_f32_16x16x32_bf16 v[150:153], v[202:205], v[190:193], v[150:153]
	s_waitcnt lgkmcnt(0)
	v_mfma_f32_16x16x32_bf16 v[154:157], v[206:209], v[174:177], v[154:157]
	v_mfma_f32_16x16x32_bf16 v[158:161], v[206:209], v[190:193], v[158:161]
	s_setprio 0
	s_nop 6
	v_max3_f32 v194, v130, v131, v132
	v_max3_f32 v195, v134, v135, v136
	v_max3_f32 v194, v194, v133, v138
	v_max3_f32 v195, v195, v137, v142
	v_max3_f32 v194, v194, v139, v140
	v_max3_f32 v195, v195, v143, v144
	v_max3_f32 v194, v194, v141, v146
	v_max3_f32 v195, v195, v145, v150
	v_max3_f32 v194, v194, v147, v148
	v_max3_f32 v195, v195, v151, v152
	v_max3_f32 v194, v194, v149, v154
	v_max3_f32 v195, v195, v153, v158
	v_max3_f32 v194, v194, v155, v156
	v_max3_f32 v195, v195, v159, v160
	v_max_f32_e32 v194, v194, v157
	v_max_f32_e32 v195, v195, v161
	v_max_f32_e32 v196, v194, v195
	v_cmp_nge_f32_e32 vcc, 0x4138aa3b, v196
	s_cbranch_vccnz .Lat_x_rare
	s_cmp_lg_u32 s13, 2
	s_cbranch_scc1 .Lat_x_noresc

; __device__ __forceinline__ void qkt(f32x16& p0, f32x16& p1, const bf16_t* Ks, const bf16x8* qr, int r32, int hi) {
;   p0 = f32x16{}; p1 = f32x16{};
;   for (int d0 = 0; d0 < 8; ++d0) { int cb = (d0 * 16 + hi * 8) * 2;
;     bf16x8 b0 = *reinterpret_cast<const bf16x8*>((const char*)Ks + KSWZ(r32, cb));
;     bf16x8 b1 = *reinterpret_cast<const bf16x8*>((const char*)Ks + KSWZ(32 + r32, cb));
; __device__ __forceinline__ void attn_body256(const bf16_t* __restrict__ Qb, const bf16_t* __restrict__ Kh, const bf16_t* __restrict__ Vh,
;                                              bf16_t* Ob, int seq, unsigned char* lds, float lam, int MODE, bf16_t* Ab, const float* wsub) {
;     ...
;     pv_all(o, vb0 + b * A2_VBUF, pa0, pa1, pa2, pa3);
;     asm volatile("s_waitcnt vmcnt(0)" ::: "memory"); __syncthreads();
;     if (j + 2 < NT) A2_DMA(j + 2, b);
.Lat_y_kpre:
	s_add_i32 s8, s13, -2
	s_and_b32 s8, s8, 1
	s_lshl_b32 s8, s8, 14
	s_add_i32 s8, s8, 0x10000
	v_add_u32_e32 v230, s8, v232
	v_add_u32_e32 v247, s8, v233
	v_add_u32_e32 v228, s8, v246
	v_add_u32_e32 v245, s8, v249
	ds_read_b128 v[194:197], v230
	ds_read_b128 v[198:201], v230 offset:4096
	ds_read_b128 v[202:205], v230 offset:8192
	ds_read_b128 v[206:209], v230 offset:12288
	ds_read_b128 v[210:213], v247
	ds_read_b128 v[214:217], v247 offset:4096
	s_cmp_eq_u32 s13, 2
	s_cbranch_scc1 .Lat_y_nodma
	s_cmp_gt_u32 s13, s19
	s_cbranch_scc1 .Lat_y_nodma
	s_sub_u32 s16, s14, 0x40000
	s_subb_u32 s17, s15, 0
	s_add_i32 s9, s22, s24
	s_add_i32 s8, s21, s99
	s_mov_b32 m0, s9
	s_nop 0
	global_load_lds_dwordx4 v220, s[16:17]
	s_add_i32 m0, s9, 0x2000
	s_nop 0
	global_load_lds_dwordx4 v221, s[16:17]
	s_sub_u32 s16, s66, 0x40000
	s_subb_u32 s17, s67, 0
	s_mov_b32 m0, s8
	s_nop 0
	global_load_lds_dwordx4 v222, s[16:17]
	s_add_i32 m0, s8, 0x2000
	s_nop 0
	global_load_lds_dwordx4 v223, s[16:17]
	s_add_u32 s16, s16, 0x100
	s_addc_u32 s17, s17, 0
	s_add_i32 m0, s8, 0x4000
	s_nop 0
	global_load_lds_dwordx4 v222, s[16:17]
	s_add_i32 m0, s8, 0x6000
	s_nop 0
	global_load_lds_dwordx4 v223, s[16:17]
